# dense attention: K LDS prefetch moved ahead of the scale-fma block in the softmax segment, rest as v64
# baseline (speedup 1.0000x reference)
; __device__ __forceinline__ void partialSM(f32x16& p0, f32x16& p1, float& m_reg, float& mn, float& alpha) {
;   constexpr float C = SCALE * 1.4426950408889634f;
;   float pmax = p0[0];
; #pragma unroll
;   for (int r = 1; r < 16; ++r) pmax = fmaxf(pmax, p0[r]);
; #pragma unroll
;   for (int r = 0; r < 16; ++r) pmax = fmaxf(pmax, p1[r]);
;   { auto rr = __builtin_amdgcn_permlane32_swap(__float_as_uint(pmax), __float_as_uint(pmax), false, false);
;     pmax = fmaxf(__uint_as_float(rr[0]), __uint_as_float(rr[1])); }
;   if (__builtin_expect(__all(pmax - m_reg <= THR / SCALE), 1)) { mn = m_reg; alpha = 1.f; }
;   else { mn = fmaxf(m_reg, pmax); alpha = __builtin_amdgcn_exp2f((m_reg - mn) * C); m_reg = mn; }
;   float mnC = -mn * C;
; #pragma unroll
;   for (int r = 0; r < 16; ++r) p0[r] = fmaf(p0[r], C, mnC);
; #pragma unroll
;   for (int r = 0; r < 16; ++r) p1[r] = fmaf(p1[r], C, mnC);
; #pragma unroll
;   for (int r = 0; r < 16; ++r) p0[r] = __builtin_amdgcn_exp2f(p0[r]);
; }
; __device__ __forceinline__ void finishSM(f32x16& p0, f32x16& p1, float alpha, float& l_reg, bf16x8& pa0, bf16x8& pa1, bf16x8& pa2, bf16x8& pa3) {
; #pragma unroll
;   for (int r = 0; r < 16; ++r) p1[r] = __builtin_amdgcn_exp2f(p1[r]);
;   float ps = 0;
; #pragma unroll
;   for (int r = 0; r < 16; ++r) ps += p0[r];
; #pragma unroll
;   for (int r = 0; r < 16; ++r) ps += p1[r];
;   { auto rr = __builtin_amdgcn_permlane32_swap(__float_as_uint(ps), __float_as_uint(ps), false, false);
;     ps = __uint_as_float(rr[0]) + __uint_as_float(rr[1]); }
;   l_reg = l_reg * alpha + ps;
;     ...
;   PK4(p0, 0, pa0); PK4(p0, 8, pa1); PK4(p1, 0, pa2); PK4(p1, 8, pa3);
;     ...
; }
.Lda_y0:
	s_barrier
	v_max3_f32 v190, v80, v81, v82
	v_max3_f32 v191, v64, v65, v66
	v_max3_f32 v190, v190, v83, v84
	v_max3_f32 v191, v191, v67, v68
	v_max3_f32 v190, v190, v85, v86
	v_max3_f32 v191, v191, v69, v70
	v_max3_f32 v190, v190, v87, v88
	v_max3_f32 v191, v191, v71, v72
	v_max3_f32 v190, v190, v89, v90
	v_max3_f32 v191, v191, v73, v74
	v_max3_f32 v190, v190, v91, v92
	v_max3_f32 v191, v191, v75, v76
	v_max3_f32 v190, v190, v93, v94
	v_max3_f32 v191, v191, v77, v78
	v_max3_f32 v190, v190, v95, v79
	v_max_f32_e32 v190, v190, v191
	v_sub_f32_e32 v215, v190, v174
	v_cmp_ge_f32_e32 vcc, s86, v215
	s_nop 0
	s_cmp_eq_u64 vcc, exec
	s_cbranch_scc1 .Lda_common_0
	v_mov_b32_e32 v191, v190
	s_nop 1
	v_permlane32_swap_b32_e32 v190, v191
	s_nop 0
	v_max_f32_e32 v212, v190, v191
	v_max_f32_e32 v191, v174, v212
	v_sub_f32_e32 v215, v174, v191
	v_mul_f32_e32 v215, s92, v215
	v_exp_f32_e32 v213, v215
	v_mov_b32_e32 v174, v191
	v_mul_f32_e32 v214, 0xbe0293ee, v174
	v_mul_f32_e32 v175, v175, v213
	s_and_saveexec_b64 s[12:13], s[40:41]
	ds_write_b32 v199, v213 offset:128
	s_or_b64 exec, exec, s[12:13]
	s_waitcnt lgkmcnt(0)
	v_add_u32_e32 v215, v99, v96
	ds_read_b128 v[228:231], v215 offset:128
	ds_read_b128 v[232:235], v215 offset:160
	ds_read_b128 v[236:239], v215 offset:192
	ds_read_b128 v[240:243], v215 offset:224
	s_waitcnt lgkmcnt(0)
	v_pk_mul_f32 v[0:1], v[0:1], v[228:229]
	v_pk_mul_f32 v[2:3], v[2:3], v[230:231]
	v_pk_mul_f32 v[4:5], v[4:5], v[232:233]
	v_pk_mul_f32 v[6:7], v[6:7], v[234:235]
	v_pk_mul_f32 v[8:9], v[8:9], v[236:237]
	v_pk_mul_f32 v[10:11], v[10:11], v[238:239]
	v_pk_mul_f32 v[12:13], v[12:13], v[240:241]
	v_pk_mul_f32 v[14:15], v[14:15], v[242:243]
	v_pk_mul_f32 v[48:49], v[48:49], v[228:229]
	v_pk_mul_f32 v[50:51], v[50:51], v[230:231]
	v_pk_mul_f32 v[52:53], v[52:53], v[232:233]
	v_pk_mul_f32 v[54:55], v[54:55], v[234:235]
	v_pk_mul_f32 v[56:57], v[56:57], v[236:237]
	v_pk_mul_f32 v[58:59], v[58:59], v[238:239]
	v_pk_mul_f32 v[60:61], v[60:61], v[240:241]
	v_pk_mul_f32 v[62:63], v[62:63], v[242:243]
	v_pk_mul_f32 v[32:33], v[32:33], v[228:229]
	v_pk_mul_f32 v[34:35], v[34:35], v[230:231]
	v_pk_mul_f32 v[36:37], v[36:37], v[232:233]
	v_pk_mul_f32 v[38:39], v[38:39], v[234:235]
	v_pk_mul_f32 v[40:41], v[40:41], v[236:237]
	v_pk_mul_f32 v[42:43], v[42:43], v[238:239]
	v_pk_mul_f32 v[44:45], v[44:45], v[240:241]
	v_pk_mul_f32 v[46:47], v[46:47], v[242:243]
	v_pk_mul_f32 v[16:17], v[16:17], v[228:229]
	v_pk_mul_f32 v[18:19], v[18:19], v[230:231]
	v_pk_mul_f32 v[20:21], v[20:21], v[232:233]
	v_pk_mul_f32 v[22:23], v[22:23], v[234:235]
	v_pk_mul_f32 v[24:25], v[24:25], v[236:237]
	v_pk_mul_f32 v[26:27], v[26:27], v[238:239]
	v_pk_mul_f32 v[28:29], v[28:29], v[240:241]
	v_pk_mul_f32 v[30:31], v[30:31], v[242:243]
.Lda_common_0:
	s_cmp_lt_u32 s31, 131
	s_cbranch_scc0 .Lda_skipk_0
	ds_read_b128 v[150:153], v204 offset:16384
	ds_read_b128 v[154:157], v204 offset:24576
	ds_read_b128 v[158:161], v205 offset:16384
	ds_read_b128 v[162:165], v205 offset:24576
	ds_read_b128 v[228:231], v206 offset:16384
	ds_read_b128 v[232:235], v206 offset:24576
	ds_read_b128 v[236:239], v207 offset:16384
	ds_read_b128 v[240:243], v207 offset:24576
.Lda_skipk_0:
	v_fma_f32 v80, v80, s92, v214
	v_fma_f32 v81, v81, s92, v214
	v_fma_f32 v82, v82, s92, v214
	v_fma_f32 v83, v83, s92, v214
	v_fma_f32 v84, v84, s92, v214
	v_fma_f32 v85, v85, s92, v214
	v_fma_f32 v86, v86, s92, v214
	v_fma_f32 v87, v87, s92, v214
	v_fma_f32 v88, v88, s92, v214
	v_fma_f32 v89, v89, s92, v214
	v_fma_f32 v90, v90, s92, v214
	v_fma_f32 v91, v91, s92, v214
	v_fma_f32 v92, v92, s92, v214
	v_fma_f32 v93, v93, s92, v214
	v_fma_f32 v94, v94, s92, v214
	v_fma_f32 v95, v95, s92, v214
	v_fma_f32 v64, v64, s92, v214
	v_fma_f32 v65, v65, s92, v214
	v_fma_f32 v66, v66, s92, v214
	v_fma_f32 v67, v67, s92, v214
	v_fma_f32 v68, v68, s92, v214
	v_fma_f32 v69, v69, s92, v214
	v_fma_f32 v70, v70, s92, v214
	v_fma_f32 v71, v71, s92, v214
	v_fma_f32 v72, v72, s92, v214
	v_fma_f32 v73, v73, s92, v214
	v_fma_f32 v74, v74, s92, v214
	v_fma_f32 v75, v75, s92, v214
	v_fma_f32 v76, v76, s92, v214
	v_fma_f32 v77, v77, s92, v214
	v_fma_f32 v78, v78, s92, v214
	v_fma_f32 v79, v79, s92, v214
.Lda_noresc_0:
	v_exp_f32_e32 v80, v80
	v_exp_f32_e32 v81, v81
	v_exp_f32_e32 v82, v82
	v_exp_f32_e32 v83, v83
	v_exp_f32_e32 v84, v84
	v_exp_f32_e32 v85, v85
	v_exp_f32_e32 v86, v86
	v_exp_f32_e32 v87, v87
	v_exp_f32_e32 v88, v88
	v_exp_f32_e32 v89, v89
	v_exp_f32_e32 v90, v90
	v_exp_f32_e32 v91, v91
	v_exp_f32_e32 v92, v92
	v_exp_f32_e32 v93, v93
	v_exp_f32_e32 v94, v94
	v_exp_f32_e32 v95, v95
	v_exp_f32_e32 v64, v64
	v_exp_f32_e32 v65, v65
	v_exp_f32_e32 v66, v66
	v_exp_f32_e32 v67, v67
	v_exp_f32_e32 v68, v68
	v_exp_f32_e32 v69, v69
	v_exp_f32_e32 v70, v70
	v_exp_f32_e32 v71, v71
	v_exp_f32_e32 v72, v72
	v_exp_f32_e32 v73, v73
	v_exp_f32_e32 v74, v74
	v_exp_f32_e32 v75, v75
	v_exp_f32_e32 v76, v76
	v_exp_f32_e32 v77, v77
	v_exp_f32_e32 v78, v78
	v_exp_f32_e32 v79, v79
	v_add_f32_e32 v190, v80, v81
	v_add_f32_e32 v191, v82, v83
	v_add_f32_e32 v190, v190, v84
	v_add_f32_e32 v191, v191, v85
	v_add_f32_e32 v190, v190, v86
	v_add_f32_e32 v191, v191, v87
	v_add_f32_e32 v190, v190, v88
	v_add_f32_e32 v191, v191, v89
	v_add_f32_e32 v190, v190, v90
	v_add_f32_e32 v191, v191, v91
	v_add_f32_e32 v190, v190, v92
	v_add_f32_e32 v191, v191, v93
	v_add_f32_e32 v190, v190, v94
	v_add_f32_e32 v191, v191, v95
	v_add_f32_e32 v190, v190, v64
	v_add_f32_e32 v191, v191, v65
	v_add_f32_e32 v190, v190, v66
	v_add_f32_e32 v191, v191, v67
	v_add_f32_e32 v190, v190, v68
	v_add_f32_e32 v191, v191, v69
	v_add_f32_e32 v190, v190, v70
	v_add_f32_e32 v191, v191, v71
	v_add_f32_e32 v190, v190, v72
	v_add_f32_e32 v191, v191, v73
	v_add_f32_e32 v190, v190, v74
	v_add_f32_e32 v191, v191, v75
	v_add_f32_e32 v190, v190, v76
	v_add_f32_e32 v191, v191, v77
	v_add_f32_e32 v190, v190, v78
	v_add_f32_e32 v191, v191, v79
	v_add_f32_e32 v190, v190, v191
	v_cvt_pk_bf16_f32 v166, v80, v81
	v_cvt_pk_bf16_f32 v167, v82, v83
	v_cvt_pk_bf16_f32 v168, v84, v85
	v_cvt_pk_bf16_f32 v169, v86, v87
	v_cvt_pk_bf16_f32 v170, v88, v89
	v_cvt_pk_bf16_f32 v171, v90, v91
	v_cvt_pk_bf16_f32 v172, v92, v93
	v_cvt_pk_bf16_f32 v173, v94, v95
	v_cvt_pk_bf16_f32 v176, v64, v65
	v_cvt_pk_bf16_f32 v177, v66, v67
	v_cvt_pk_bf16_f32 v178, v68, v69
	v_cvt_pk_bf16_f32 v179, v70, v71
	v_cvt_pk_bf16_f32 v180, v72, v73
	v_cvt_pk_bf16_f32 v181, v74, v75
	v_cvt_pk_bf16_f32 v182, v76, v77
	v_cvt_pk_bf16_f32 v183, v78, v79
	v_permlane32_swap_b32_e32 v166, v168
	v_permlane32_swap_b32_e32 v167, v169
	v_permlane32_swap_b32_e32 v170, v172
	v_permlane32_swap_b32_e32 v171, v173
	v_permlane32_swap_b32_e32 v176, v178
	v_permlane32_swap_b32_e32 v177, v179
	v_permlane32_swap_b32_e32 v180, v182
	v_permlane32_swap_b32_e32 v181, v183
	v_add_f32_e32 v175, v175, v190
	s_add_u32 s31, s31, 1
	s_barrier
; #define SBAR() __builtin_amdgcn_sched_barrier(0)
; __device__ __forceinline__ void qkt(f32x16& p0, f32x16& p1, const bf16_t* Ks, const bf16x8* qr, int r32, int hi) {
;   p0 = f32x16{}; p1 = f32x16{};
; #pragma unroll
;   for (int d0 = 0; d0 < 8; ++d0) { int cb = (d0 * 16 + hi * 8) * 2;
;     bf16x8 b0 = *reinterpret_cast<const bf16x8*>((const char*)Ks + KSWZ(r32, cb));
;     bf16x8 b1 = *reinterpret_cast<const bf16x8*>((const char*)Ks + KSWZ(32 + r32, cb));
;     p0 = __builtin_amdgcn_mfma_f32_32x32x16_bf16(b0, qr[d0], p0, 0, 0, 0);
;     p1 = __builtin_amdgcn_mfma_f32_32x32x16_bf16(b1, qr[d0], p1, 0, 0, 0); }
; }
; __device__ __forceinline__ int v_st(int k, int c) { const int kk = (k & ~0xC) | ((k & 4) << 1) | ((k & 8) >> 1); return ((kk >> 3) * 4 + (c >> 5)) * 512 + ((kk & 7) * 32 + (c & 31)) * 2; }
; __device__ __forceinline__ int v_rd_base(int lane) { return ((lane & 3) << 3) | (((lane >> 2) & 3) << 6) | (((lane >> 4) & 1) << 5) | (((lane >> 5) & 1) << 8); }
; template <int OFF> __device__ __forceinline__ s16x4 tr_read(int vb) {
;   s16x4 r; asm volatile("ds_read_b64_tr_b16 %0, %1 offset:%2" : "=&v"(r) : "v"(vb), "i"(OFF) : "memory"); return r;
; }
; template <int D0> __device__ __forceinline__ void pv_one(f32x16& od, int vb, bf16x8 pa0, bf16x8 pa1, bf16x8 pa2, bf16x8 pa3) {
;   const s16x4 l0 = tr_read<v_rd_off(D0, 0, 0)>(vb), h0 = tr_read<v_rd_off(D0, 0, 1)>(vb), l1 = tr_read<v_rd_off(D0, 1, 0)>(vb), h1 = tr_read<v_rd_off(D0, 1, 1)>(vb);
;   const s16x4 l2 = tr_read<v_rd_off(D0, 2, 0)>(vb), h2 = tr_read<v_rd_off(D0, 2, 1)>(vb), l3 = tr_read<v_rd_off(D0, 3, 0)>(vb), h3 = tr_read<v_rd_off(D0, 3, 1)>(vb);
;   asm volatile("s_waitcnt lgkmcnt(0)" ::: "memory"); SBAR();
;     ...
;   od = __builtin_amdgcn_mfma_f32_32x32x16_bf16(pa0, PK(l0, h0), od, 0, 0, 0);
;   od = __builtin_amdgcn_mfma_f32_32x32x16_bf16(pa1, PK(l1, h1), od, 0, 0, 0);
;   od = __builtin_amdgcn_mfma_f32_32x32x16_bf16(pa2, PK(l2, h2), od, 0, 0, 0);
;   od = __builtin_amdgcn_mfma_f32_32x32x16_bf16(pa3, PK(l3, h3), od, 0, 0, 0);
;     ...
; }
; __device__ __forceinline__ void pv_d0(f32x16* o, int vb, bf16x8 pa0, bf16x8 pa1, bf16x8 pa2, bf16x8 pa3) {
;   pv_one<0>(o[0], vb, pa0, pa1, pa2, pa3); pv_one<1>(o[1], vb, pa0, pa1, pa2, pa3); pv_one<2>(o[2], vb, pa0, pa1, pa2, pa3); pv_one<3>(o[3], vb, pa0, pa1, pa2, pa3);
	s_setprio 3
	s_waitcnt vmcnt(4)
	ds_write_b128 v197, v[186:189] offset:49152
	ds_write_b128 v197, v[220:223] offset:57344
	ds_write_b128 v185, v[246:249] offset:49152
	ds_write_b128 v185, v[200:203] offset:57344
	s_waitcnt lgkmcnt(10)
	v_mfma_f32_32x32x16_bf16 v[80:95], v[150:153], v[130:133], 0
	v_mfma_f32_32x32x16_bf16 v[64:79], v[154:157], v[130:133], 0
	global_load_dwordx4 v[186:189], v184, s[16:17]
	global_load_dwordx4 v[220:223], v184, s[2:3]
	global_load_dwordx4 v[246:249], v184, s[14:15]
	global_load_dwordx4 v[200:203], v184, s[10:11]
	s_add_u32 s16, s16, 0x60000
	s_addc_u32 s17, s17, 0
	s_add_u32 s2, s2, 0x60000
	s_addc_u32 s3, s3, 0
	s_add_u32 s14, s14, 0x60000
	s_addc_u32 s15, s15, 0
	s_add_u32 s10, s10, 0x60000
	s_addc_u32 s11, s11, 0
	ds_read_b128 v[150:153], v208 offset:16384
	ds_read_b128 v[154:157], v208 offset:24576
	s_waitcnt lgkmcnt(10)
	v_mfma_f32_32x32x16_bf16 v[80:95], v[158:161], v[126:129], v[80:95]
	v_mfma_f32_32x32x16_bf16 v[64:79], v[162:165], v[126:129], v[64:79]
	ds_read_b128 v[158:161], v209 offset:16384
	ds_read_b128 v[162:165], v209 offset:24576
	s_waitcnt lgkmcnt(10)
	v_mfma_f32_32x32x16_bf16 v[80:95], v[228:231], v[122:125], v[80:95]
	v_mfma_f32_32x32x16_bf16 v[64:79], v[232:235], v[122:125], v[64:79]
	ds_read_b128 v[228:231], v210 offset:16384
	ds_read_b128 v[232:235], v210 offset:24576
	s_waitcnt lgkmcnt(10)
	v_mfma_f32_32x32x16_bf16 v[80:95], v[236:239], v[118:121], v[80:95]
	v_mfma_f32_32x32x16_bf16 v[64:79], v[240:243], v[118:121], v[64:79]
	ds_read_b128 v[236:239], v211 offset:16384
	ds_read_b128 v[240:243], v211 offset:24576
	s_waitcnt lgkmcnt(6)
	v_mfma_f32_32x32x16_bf16 v[80:95], v[150:153], v[114:117], v[80:95]
	v_mfma_f32_32x32x16_bf16 v[64:79], v[154:157], v[114:117], v[64:79]
	ds_read_b64_tr_b16 v[150:151], v196 offset:0
	ds_read_b64_tr_b16 v[152:153], v196 offset:2048
	ds_read_b64_tr_b16 v[154:155], v196 offset:4096
	ds_read_b64_tr_b16 v[156:157], v196 offset:6144
	s_waitcnt lgkmcnt(8)
	v_mfma_f32_32x32x16_bf16 v[80:95], v[158:161], v[110:113], v[80:95]
	v_mfma_f32_32x32x16_bf16 v[64:79], v[162:165], v[110:113], v[64:79]
	ds_read_b64_tr_b16 v[158:159], v196 offset:8192
	ds_read_b64_tr_b16 v[160:161], v196 offset:10240
	ds_read_b64_tr_b16 v[162:163], v196 offset:12288
	ds_read_b64_tr_b16 v[164:165], v196 offset:14336
	s_waitcnt lgkmcnt(10)
	v_mfma_f32_32x32x16_bf16 v[80:95], v[228:231], v[106:109], v[80:95]
	v_mfma_f32_32x32x16_bf16 v[64:79], v[232:235], v[106:109], v[64:79]
	ds_read_b64_tr_b16 v[228:229], v196 offset:512
	ds_read_b64_tr_b16 v[230:231], v196 offset:2560
	ds_read_b64_tr_b16 v[232:233], v196 offset:4608
	ds_read_b64_tr_b16 v[234:235], v196 offset:6656
	s_waitcnt lgkmcnt(12)
	v_mfma_f32_32x32x16_bf16 v[80:95], v[236:239], v[102:105], v[80:95]
	v_mfma_f32_32x32x16_bf16 v[64:79], v[240:243], v[102:105], v[64:79]
	ds_read_b64_tr_b16 v[236:237], v196 offset:8704
	ds_read_b64_tr_b16 v[238:239], v196 offset:10752
	s_waitcnt lgkmcnt(12)
	v_mfma_f32_32x32x16_bf16 v[0:15], v[166:169], v[150:153], v[0:15]
	ds_read_b64_tr_b16 v[240:241], v196 offset:12800
	ds_read_b64_tr_b16 v[242:243], v196 offset:14848
	s_waitcnt lgkmcnt(12)
	v_mfma_f32_32x32x16_bf16 v[0:15], v[170:173], v[154:157], v[0:15]
	ds_read_b64_tr_b16 v[150:151], v196 offset:1024
	ds_read_b64_tr_b16 v[152:153], v196 offset:3072
	s_waitcnt lgkmcnt(12)
	v_mfma_f32_32x32x16_bf16 v[0:15], v[176:179], v[158:161], v[0:15]
	ds_read_b64_tr_b16 v[154:155], v196 offset:5120
	ds_read_b64_tr_b16 v[156:157], v196 offset:7168
	s_waitcnt lgkmcnt(12)
	v_mfma_f32_32x32x16_bf16 v[0:15], v[180:183], v[162:165], v[0:15]
	ds_read_b64_tr_b16 v[158:159], v196 offset:9216
	ds_read_b64_tr_b16 v[160:161], v196 offset:11264
	s_waitcnt lgkmcnt(12)
	v_mfma_f32_32x32x16_bf16 v[48:63], v[166:169], v[228:231], v[48:63]
	ds_read_b64_tr_b16 v[162:163], v196 offset:13312
	ds_read_b64_tr_b16 v[164:165], v196 offset:15360
	s_waitcnt lgkmcnt(12)
	v_mfma_f32_32x32x16_bf16 v[48:63], v[170:173], v[232:235], v[48:63]
	ds_read_b64_tr_b16 v[228:229], v196 offset:1536
	ds_read_b64_tr_b16 v[230:231], v196 offset:3584
	s_waitcnt lgkmcnt(12)
	v_mfma_f32_32x32x16_bf16 v[48:63], v[176:179], v[236:239], v[48:63]
	ds_read_b64_tr_b16 v[232:233], v196 offset:5632
	ds_read_b64_tr_b16 v[234:235], v196 offset:7680
	s_waitcnt lgkmcnt(12)
	v_mfma_f32_32x32x16_bf16 v[48:63], v[180:183], v[240:243], v[48:63]
	ds_read_b64_tr_b16 v[236:237], v196 offset:9728
	ds_read_b64_tr_b16 v[238:239], v196 offset:11776
	s_waitcnt lgkmcnt(12)
	v_mfma_f32_32x32x16_bf16 v[32:47], v[166:169], v[150:153], v[32:47]
	ds_read_b64_tr_b16 v[240:241], v196 offset:13824
	ds_read_b64_tr_b16 v[242:243], v196 offset:15872
	s_waitcnt lgkmcnt(12)
	v_mfma_f32_32x32x16_bf16 v[32:47], v[170:173], v[154:157], v[32:47]
	s_waitcnt lgkmcnt(10)
	v_mfma_f32_32x32x16_bf16 v[32:47], v[176:179], v[158:161], v[32:47]
	s_waitcnt lgkmcnt(8)
	v_mfma_f32_32x32x16_bf16 v[32:47], v[180:183], v[162:165], v[32:47]
	s_waitcnt lgkmcnt(6)
	v_mfma_f32_32x32x16_bf16 v[16:31], v[166:169], v[228:231], v[16:31]
	s_waitcnt lgkmcnt(4)
	v_mfma_f32_32x32x16_bf16 v[16:31], v[170:173], v[232:235], v[16:31]
	s_waitcnt lgkmcnt(2)
	v_mfma_f32_32x32x16_bf16 v[16:31], v[176:179], v[236:239], v[16:31]
	s_waitcnt lgkmcnt(0)
	v_mfma_f32_32x32x16_bf16 v[16:31], v[180:183], v[240:243], v[16:31]
	s_setprio 0
	s_barrier
	v_max3_f32 v190, v80, v81, v82
	v_max3_f32 v191, v64, v65, v66
	v_max3_f32 v190, v190, v83, v84
	v_max3_f32 v191, v191, v67, v68
	v_max3_f32 v190, v190, v85, v86
	v_max3_f32 v191, v191, v69, v70
	v_max3_f32 v190, v190, v87, v88
	v_max3_f32 v191, v191, v71, v72
	v_max3_f32 v190, v190, v89, v90
	v_max3_f32 v191, v191, v73, v74
	v_max3_f32 v190, v190, v91, v92
	v_max3_f32 v191, v191, v75, v76
	v_max3_f32 v190, v190, v93, v94
	v_max3_f32 v191, v191, v77, v78
	v_max3_f32 v190, v190, v95, v79
	v_max_f32_e32 v190, v190, v191
	v_sub_f32_e32 v215, v190, v174
	v_cmp_ge_f32_e32 vcc, s86, v215
	s_nop 0
	s_cmp_eq_u64 vcc, exec
	s_cbranch_scc1 .Lda_common_1
; __device__ __forceinline__ void partialSM(f32x16& p0, f32x16& p1, float& m_reg, float& mn, float& alpha) {
;     ...
;   if (__builtin_expect(__all(pmax - m_reg <= THR / SCALE), 1)) { mn = m_reg; alpha = 1.f; }
;   else { mn = fmaxf(m_reg, pmax); alpha = __builtin_amdgcn_exp2f((m_reg - mn) * C); m_reg = mn; }
;   float mnC = -mn * C;
; #pragma unroll
;   for (int r = 0; r < 16; ++r) p0[r] = fmaf(p0[r], C, mnC);
; #pragma unroll
;   for (int r = 0; r < 16; ++r) p1[r] = fmaf(p1[r], C, mnC);
; #pragma unroll
;   for (int r = 0; r < 16; ++r) p0[r] = __builtin_amdgcn_exp2f(p0[r]);
; }
; __device__ __forceinline__ void finishSM(f32x16& p0, f32x16& p1, float alpha, float& l_reg, bf16x8& pa0, bf16x8& pa1, bf16x8& pa2, bf16x8& pa3) {
; #pragma unroll
;   for (int r = 0; r < 16; ++r) p1[r] = __builtin_amdgcn_exp2f(p1[r]);
;   float ps = 0;
; #pragma unroll
;   for (int r = 0; r < 16; ++r) ps += p0[r];
; #pragma unroll
;   for (int r = 0; r < 16; ++r) ps += p1[r];
;   { auto rr = __builtin_amdgcn_permlane32_swap(__float_as_uint(ps), __float_as_uint(ps), false, false);
;     ps = __uint_as_float(rr[0]) + __uint_as_float(rr[1]); }
;   l_reg = l_reg * alpha + ps;
;     ...
;   PK4(p0, 0, pa0); PK4(p0, 8, pa1); PK4(p1, 0, pa2); PK4(p1, 8, pa3);
;     ...
; }
	v_mov_b32_e32 v191, v190
	s_nop 1
	v_permlane32_swap_b32_e32 v190, v191
	s_nop 0
	v_max_f32_e32 v212, v190, v191
	v_max_f32_e32 v191, v174, v212
	v_sub_f32_e32 v215, v174, v191
	v_mul_f32_e32 v215, s92, v215
	v_exp_f32_e32 v213, v215
	v_mov_b32_e32 v174, v191
	v_mul_f32_e32 v214, 0xbe0293ee, v174
	v_mul_f32_e32 v175, v175, v213
	s_and_saveexec_b64 s[12:13], s[40:41]
	ds_write_b32 v199, v213 offset:128
	s_or_b64 exec, exec, s[12:13]
	s_waitcnt lgkmcnt(0)
	v_add_u32_e32 v215, v99, v96
	ds_read_b128 v[228:231], v215 offset:128
	ds_read_b128 v[232:235], v215 offset:160
	ds_read_b128 v[236:239], v215 offset:192
	ds_read_b128 v[240:243], v215 offset:224
	s_waitcnt lgkmcnt(0)
	v_pk_mul_f32 v[0:1], v[0:1], v[228:229]
	v_pk_mul_f32 v[2:3], v[2:3], v[230:231]
	v_pk_mul_f32 v[4:5], v[4:5], v[232:233]
	v_pk_mul_f32 v[6:7], v[6:7], v[234:235]
	v_pk_mul_f32 v[8:9], v[8:9], v[236:237]
	v_pk_mul_f32 v[10:11], v[10:11], v[238:239]
	v_pk_mul_f32 v[12:13], v[12:13], v[240:241]
	v_pk_mul_f32 v[14:15], v[14:15], v[242:243]
	v_pk_mul_f32 v[48:49], v[48:49], v[228:229]
	v_pk_mul_f32 v[50:51], v[50:51], v[230:231]
	v_pk_mul_f32 v[52:53], v[52:53], v[232:233]
	v_pk_mul_f32 v[54:55], v[54:55], v[234:235]
	v_pk_mul_f32 v[56:57], v[56:57], v[236:237]
	v_pk_mul_f32 v[58:59], v[58:59], v[238:239]
	v_pk_mul_f32 v[60:61], v[60:61], v[240:241]
	v_pk_mul_f32 v[62:63], v[62:63], v[242:243]
	v_pk_mul_f32 v[32:33], v[32:33], v[228:229]
	v_pk_mul_f32 v[34:35], v[34:35], v[230:231]
	v_pk_mul_f32 v[36:37], v[36:37], v[232:233]
	v_pk_mul_f32 v[38:39], v[38:39], v[234:235]
	v_pk_mul_f32 v[40:41], v[40:41], v[236:237]
	v_pk_mul_f32 v[42:43], v[42:43], v[238:239]
	v_pk_mul_f32 v[44:45], v[44:45], v[240:241]
	v_pk_mul_f32 v[46:47], v[46:47], v[242:243]
	v_pk_mul_f32 v[16:17], v[16:17], v[228:229]
	v_pk_mul_f32 v[18:19], v[18:19], v[230:231]
	v_pk_mul_f32 v[20:21], v[20:21], v[232:233]
	v_pk_mul_f32 v[22:23], v[22:23], v[234:235]
	v_pk_mul_f32 v[24:25], v[24:25], v[236:237]
	v_pk_mul_f32 v[26:27], v[26:27], v[238:239]
	v_pk_mul_f32 v[28:29], v[28:29], v[240:241]
	v_pk_mul_f32 v[30:31], v[30:31], v[242:243]
.Lda_common_1:
	s_cmp_lt_u32 s31, 131
	s_cbranch_scc0 .Lda_skipk_1
	ds_read_b128 v[150:153], v204 offset:32768
	ds_read_b128 v[154:157], v204 offset:40960
	ds_read_b128 v[158:161], v205 offset:32768
	ds_read_b128 v[162:165], v205 offset:40960
	ds_read_b128 v[228:231], v206 offset:32768
	ds_read_b128 v[232:235], v206 offset:40960
	ds_read_b128 v[236:239], v207 offset:32768
	ds_read_b128 v[240:243], v207 offset:40960
.Lda_skipk_1:
	v_fma_f32 v80, v80, s92, v214
	v_fma_f32 v81, v81, s92, v214
	v_fma_f32 v82, v82, s92, v214
	v_fma_f32 v83, v83, s92, v214
	v_fma_f32 v84, v84, s92, v214
	v_fma_f32 v85, v85, s92, v214
	v_fma_f32 v86, v86, s92, v214
	v_fma_f32 v87, v87, s92, v214
	v_fma_f32 v88, v88, s92, v214
	v_fma_f32 v89, v89, s92, v214
	v_fma_f32 v90, v90, s92, v214
	v_fma_f32 v91, v91, s92, v214
	v_fma_f32 v92, v92, s92, v214
	v_fma_f32 v93, v93, s92, v214
	v_fma_f32 v94, v94, s92, v214
	v_fma_f32 v95, v95, s92, v214
	v_fma_f32 v64, v64, s92, v214
	v_fma_f32 v65, v65, s92, v214
	v_fma_f32 v66, v66, s92, v214
	v_fma_f32 v67, v67, s92, v214
	v_fma_f32 v68, v68, s92, v214
	v_fma_f32 v69, v69, s92, v214
	v_fma_f32 v70, v70, s92, v214
	v_fma_f32 v71, v71, s92, v214
	v_fma_f32 v72, v72, s92, v214
	v_fma_f32 v73, v73, s92, v214
	v_fma_f32 v74, v74, s92, v214
	v_fma_f32 v75, v75, s92, v214
	v_fma_f32 v76, v76, s92, v214
	v_fma_f32 v77, v77, s92, v214
	v_fma_f32 v78, v78, s92, v214
	v_fma_f32 v79, v79, s92, v214
.Lda_noresc_1:
	v_exp_f32_e32 v80, v80
	v_exp_f32_e32 v81, v81
	v_exp_f32_e32 v82, v82
	v_exp_f32_e32 v83, v83
	v_exp_f32_e32 v84, v84
	v_exp_f32_e32 v85, v85
	v_exp_f32_e32 v86, v86
	v_exp_f32_e32 v87, v87
	v_exp_f32_e32 v88, v88
	v_exp_f32_e32 v89, v89
	v_exp_f32_e32 v90, v90
	v_exp_f32_e32 v91, v91
	v_exp_f32_e32 v92, v92
	v_exp_f32_e32 v93, v93
	v_exp_f32_e32 v94, v94
	v_exp_f32_e32 v95, v95
	v_exp_f32_e32 v64, v64
	v_exp_f32_e32 v65, v65
	v_exp_f32_e32 v66, v66
	v_exp_f32_e32 v67, v67
	v_exp_f32_e32 v68, v68
	v_exp_f32_e32 v69, v69
	v_exp_f32_e32 v70, v70
	v_exp_f32_e32 v71, v71
	v_exp_f32_e32 v72, v72
	v_exp_f32_e32 v73, v73
	v_exp_f32_e32 v74, v74
	v_exp_f32_e32 v75, v75
	v_exp_f32_e32 v76, v76
	v_exp_f32_e32 v77, v77
	v_exp_f32_e32 v78, v78
	v_exp_f32_e32 v79, v79
	v_add_f32_e32 v190, v80, v81
	v_add_f32_e32 v191, v82, v83
	v_add_f32_e32 v190, v190, v84
	v_add_f32_e32 v191, v191, v85
	v_add_f32_e32 v190, v190, v86
	v_add_f32_e32 v191, v191, v87
	v_add_f32_e32 v190, v190, v88
	v_add_f32_e32 v191, v191, v89
	v_add_f32_e32 v190, v190, v90
	v_add_f32_e32 v191, v191, v91
	v_add_f32_e32 v190, v190, v92
	v_add_f32_e32 v191, v191, v93
	v_add_f32_e32 v190, v190, v94
	v_add_f32_e32 v191, v191, v95
	v_add_f32_e32 v190, v190, v64
	v_add_f32_e32 v191, v191, v65
	v_add_f32_e32 v190, v190, v66
	v_add_f32_e32 v191, v191, v67
	v_add_f32_e32 v190, v190, v68
	v_add_f32_e32 v191, v191, v69
	v_add_f32_e32 v190, v190, v70
	v_add_f32_e32 v191, v191, v71
	v_add_f32_e32 v190, v190, v72
	v_add_f32_e32 v191, v191, v73
	v_add_f32_e32 v190, v190, v74
	v_add_f32_e32 v191, v191, v75
	v_add_f32_e32 v190, v190, v76
	v_add_f32_e32 v191, v191, v77
	v_add_f32_e32 v190, v190, v78
	v_add_f32_e32 v191, v191, v79
	v_add_f32_e32 v190, v190, v191
	v_cvt_pk_bf16_f32 v166, v80, v81
	v_cvt_pk_bf16_f32 v167, v82, v83
	v_cvt_pk_bf16_f32 v168, v84, v85
	v_cvt_pk_bf16_f32 v169, v86, v87
	v_cvt_pk_bf16_f32 v170, v88, v89
	v_cvt_pk_bf16_f32 v171, v90, v91
	v_cvt_pk_bf16_f32 v172, v92, v93
	v_cvt_pk_bf16_f32 v173, v94, v95
	v_cvt_pk_bf16_f32 v176, v64, v65
	v_cvt_pk_bf16_f32 v177, v66, v67
	v_cvt_pk_bf16_f32 v178, v68, v69
	v_cvt_pk_bf16_f32 v179, v70, v71
	v_cvt_pk_bf16_f32 v180, v72, v73
	v_cvt_pk_bf16_f32 v181, v74, v75
	v_cvt_pk_bf16_f32 v182, v76, v77
	v_cvt_pk_bf16_f32 v183, v78, v79
	v_permlane32_swap_b32_e32 v166, v168
	v_permlane32_swap_b32_e32 v167, v169
	v_permlane32_swap_b32_e32 v170, v172
	v_permlane32_swap_b32_e32 v171, v173
	v_permlane32_swap_b32_e32 v176, v178
	v_permlane32_swap_b32_e32 v177, v179
	v_permlane32_swap_b32_e32 v180, v182
	v_permlane32_swap_b32_e32 v181, v183
	v_add_f32_e32 v175, v175, v190
	s_add_u32 s31, s31, 1
	s_barrier
; #define SBAR() __builtin_amdgcn_sched_barrier(0)
; __device__ __forceinline__ void qkt(f32x16& p0, f32x16& p1, const bf16_t* Ks, const bf16x8* qr, int r32, int hi) {
;   p0 = f32x16{}; p1 = f32x16{};
; #pragma unroll
;   for (int d0 = 0; d0 < 8; ++d0) { int cb = (d0 * 16 + hi * 8) * 2;
;     bf16x8 b0 = *reinterpret_cast<const bf16x8*>((const char*)Ks + KSWZ(r32, cb));
;     bf16x8 b1 = *reinterpret_cast<const bf16x8*>((const char*)Ks + KSWZ(32 + r32, cb));
;     p0 = __builtin_amdgcn_mfma_f32_32x32x16_bf16(b0, qr[d0], p0, 0, 0, 0);
;     p1 = __builtin_amdgcn_mfma_f32_32x32x16_bf16(b1, qr[d0], p1, 0, 0, 0); }
; }
; __device__ __forceinline__ int v_st(int k, int c) { const int kk = (k & ~0xC) | ((k & 4) << 1) | ((k & 8) >> 1); return ((kk >> 3) * 4 + (c >> 5)) * 512 + ((kk & 7) * 32 + (c & 31)) * 2; }
; __device__ __forceinline__ int v_rd_base(int lane) { return ((lane & 3) << 3) | (((lane >> 2) & 3) << 6) | (((lane >> 4) & 1) << 5) | (((lane >> 5) & 1) << 8); }
; template <int OFF> __device__ __forceinline__ s16x4 tr_read(int vb) {
;   s16x4 r; asm volatile("ds_read_b64_tr_b16 %0, %1 offset:%2" : "=&v"(r) : "v"(vb), "i"(OFF) : "memory"); return r;
; }
; template <int D0> __device__ __forceinline__ void pv_one(f32x16& od, int vb, bf16x8 pa0, bf16x8 pa1, bf16x8 pa2, bf16x8 pa3) {
;   const s16x4 l0 = tr_read<v_rd_off(D0, 0, 0)>(vb), h0 = tr_read<v_rd_off(D0, 0, 1)>(vb), l1 = tr_read<v_rd_off(D0, 1, 0)>(vb), h1 = tr_read<v_rd_off(D0, 1, 1)>(vb);
;   const s16x4 l2 = tr_read<v_rd_off(D0, 2, 0)>(vb), h2 = tr_read<v_rd_off(D0, 2, 1)>(vb), l3 = tr_read<v_rd_off(D0, 3, 0)>(vb), h3 = tr_read<v_rd_off(D0, 3, 1)>(vb);
;   asm volatile("s_waitcnt lgkmcnt(0)" ::: "memory"); SBAR();
;     ...
;   od = __builtin_amdgcn_mfma_f32_32x32x16_bf16(pa0, PK(l0, h0), od, 0, 0, 0);
;   od = __builtin_amdgcn_mfma_f32_32x32x16_bf16(pa1, PK(l1, h1), od, 0, 0, 0);
;   od = __builtin_amdgcn_mfma_f32_32x32x16_bf16(pa2, PK(l2, h2), od, 0, 0, 0);
;   od = __builtin_amdgcn_mfma_f32_32x32x16_bf16(pa3, PK(l3, h3), od, 0, 0, 0);
;     ...
; }
; __device__ __forceinline__ void pv_d0(f32x16* o, int vb, bf16x8 pa0, bf16x8 pa1, bf16x8 pa2, bf16x8 pa3) {
;   pv_one<0>(o[0], vb, pa0, pa1, pa2, pa3); pv_one<1>(o[1], vb, pa0, pa1, pa2, pa3); pv_one<2>(o[2], vb, pa0, pa1, pa2, pa3); pv_one<3>(o[3], vb, pa0, pa1, pa2, pa3);
	s_setprio 3
	s_waitcnt vmcnt(4)
	ds_write_b128 v197, v[134:137] offset:0
	ds_write_b128 v197, v[138:141] offset:8192
	ds_write_b128 v185, v[142:145] offset:0
	ds_write_b128 v185, v[146:149] offset:8192
	s_waitcnt lgkmcnt(10)
	v_mfma_f32_32x32x16_bf16 v[80:95], v[150:153], v[130:133], 0
	v_mfma_f32_32x32x16_bf16 v[64:79], v[154:157], v[130:133], 0
	global_load_dwordx4 v[134:137], v184, s[16:17]
	global_load_dwordx4 v[138:141], v184, s[2:3]
	global_load_dwordx4 v[142:145], v184, s[14:15]
	global_load_dwordx4 v[146:149], v184, s[10:11]
	s_add_u32 s16, s16, 0x60000
	s_addc_u32 s17, s17, 0
	s_add_u32 s2, s2, 0x60000
	s_addc_u32 s3, s3, 0
	s_add_u32 s14, s14, 0x60000
	s_addc_u32 s15, s15, 0
	s_add_u32 s10, s10, 0x60000
	s_addc_u32 s11, s11, 0
	ds_read_b128 v[150:153], v208 offset:32768
	ds_read_b128 v[154:157], v208 offset:40960
	s_waitcnt lgkmcnt(10)
	v_mfma_f32_32x32x16_bf16 v[80:95], v[158:161], v[126:129], v[80:95]
	v_mfma_f32_32x32x16_bf16 v[64:79], v[162:165], v[126:129], v[64:79]
	ds_read_b128 v[158:161], v209 offset:32768
	ds_read_b128 v[162:165], v209 offset:40960
	s_waitcnt lgkmcnt(10)
	v_mfma_f32_32x32x16_bf16 v[80:95], v[228:231], v[122:125], v[80:95]
	v_mfma_f32_32x32x16_bf16 v[64:79], v[232:235], v[122:125], v[64:79]
	ds_read_b128 v[228:231], v210 offset:32768
	ds_read_b128 v[232:235], v210 offset:40960
	s_waitcnt lgkmcnt(10)
	v_mfma_f32_32x32x16_bf16 v[80:95], v[236:239], v[118:121], v[80:95]
	v_mfma_f32_32x32x16_bf16 v[64:79], v[240:243], v[118:121], v[64:79]
	ds_read_b128 v[236:239], v211 offset:32768
	ds_read_b128 v[240:243], v211 offset:40960
	s_waitcnt lgkmcnt(6)
	v_mfma_f32_32x32x16_bf16 v[80:95], v[150:153], v[114:117], v[80:95]
	v_mfma_f32_32x32x16_bf16 v[64:79], v[154:157], v[114:117], v[64:79]
	ds_read_b64_tr_b16 v[150:151], v196 offset:16384
	ds_read_b64_tr_b16 v[152:153], v196 offset:18432
	ds_read_b64_tr_b16 v[154:155], v196 offset:20480
	ds_read_b64_tr_b16 v[156:157], v196 offset:22528
	s_waitcnt lgkmcnt(8)
	v_mfma_f32_32x32x16_bf16 v[80:95], v[158:161], v[110:113], v[80:95]
	v_mfma_f32_32x32x16_bf16 v[64:79], v[162:165], v[110:113], v[64:79]
	ds_read_b64_tr_b16 v[158:159], v196 offset:24576
	ds_read_b64_tr_b16 v[160:161], v196 offset:26624
	ds_read_b64_tr_b16 v[162:163], v196 offset:28672
	ds_read_b64_tr_b16 v[164:165], v196 offset:30720
	s_waitcnt lgkmcnt(10)
	v_mfma_f32_32x32x16_bf16 v[80:95], v[228:231], v[106:109], v[80:95]
	v_mfma_f32_32x32x16_bf16 v[64:79], v[232:235], v[106:109], v[64:79]
	ds_read_b64_tr_b16 v[228:229], v196 offset:16896
	ds_read_b64_tr_b16 v[230:231], v196 offset:18944
	ds_read_b64_tr_b16 v[232:233], v196 offset:20992
	ds_read_b64_tr_b16 v[234:235], v196 offset:23040
	s_waitcnt lgkmcnt(12)
	v_mfma_f32_32x32x16_bf16 v[80:95], v[236:239], v[102:105], v[80:95]
	v_mfma_f32_32x32x16_bf16 v[64:79], v[240:243], v[102:105], v[64:79]
	ds_read_b64_tr_b16 v[236:237], v196 offset:25088
	ds_read_b64_tr_b16 v[238:239], v196 offset:27136
	s_waitcnt lgkmcnt(12)
	v_mfma_f32_32x32x16_bf16 v[0:15], v[166:169], v[150:153], v[0:15]
	ds_read_b64_tr_b16 v[240:241], v196 offset:29184
	ds_read_b64_tr_b16 v[242:243], v196 offset:31232
	s_waitcnt lgkmcnt(12)
	v_mfma_f32_32x32x16_bf16 v[0:15], v[170:173], v[154:157], v[0:15]
	ds_read_b64_tr_b16 v[150:151], v196 offset:17408
	ds_read_b64_tr_b16 v[152:153], v196 offset:19456
	s_waitcnt lgkmcnt(12)
	v_mfma_f32_32x32x16_bf16 v[0:15], v[176:179], v[158:161], v[0:15]
	ds_read_b64_tr_b16 v[154:155], v196 offset:21504
	ds_read_b64_tr_b16 v[156:157], v196 offset:23552
	s_waitcnt lgkmcnt(12)
	v_mfma_f32_32x32x16_bf16 v[0:15], v[180:183], v[162:165], v[0:15]
	ds_read_b64_tr_b16 v[158:159], v196 offset:25600
	ds_read_b64_tr_b16 v[160:161], v196 offset:27648
	s_waitcnt lgkmcnt(12)
	v_mfma_f32_32x32x16_bf16 v[48:63], v[166:169], v[228:231], v[48:63]
	ds_read_b64_tr_b16 v[162:163], v196 offset:29696
	ds_read_b64_tr_b16 v[164:165], v196 offset:31744
	s_waitcnt lgkmcnt(12)
	v_mfma_f32_32x32x16_bf16 v[48:63], v[170:173], v[232:235], v[48:63]
	ds_read_b64_tr_b16 v[228:229], v196 offset:17920
	ds_read_b64_tr_b16 v[230:231], v196 offset:19968
	s_waitcnt lgkmcnt(12)
	v_mfma_f32_32x32x16_bf16 v[48:63], v[176:179], v[236:239], v[48:63]
	ds_read_b64_tr_b16 v[232:233], v196 offset:22016
	ds_read_b64_tr_b16 v[234:235], v196 offset:24064
	s_waitcnt lgkmcnt(12)
	v_mfma_f32_32x32x16_bf16 v[48:63], v[180:183], v[240:243], v[48:63]
	ds_read_b64_tr_b16 v[236:237], v196 offset:26112
	ds_read_b64_tr_b16 v[238:239], v196 offset:28160
	s_waitcnt lgkmcnt(12)
	v_mfma_f32_32x32x16_bf16 v[32:47], v[166:169], v[150:153], v[32:47]
	ds_read_b64_tr_b16 v[240:241], v196 offset:30208
	ds_read_b64_tr_b16 v[242:243], v196 offset:32256
	s_waitcnt lgkmcnt(12)
	v_mfma_f32_32x32x16_bf16 v[32:47], v[170:173], v[154:157], v[32:47]
	s_waitcnt lgkmcnt(10)
	v_mfma_f32_32x32x16_bf16 v[32:47], v[176:179], v[158:161], v[32:47]
	s_waitcnt lgkmcnt(8)
	v_mfma_f32_32x32x16_bf16 v[32:47], v[180:183], v[162:165], v[32:47]
	s_waitcnt lgkmcnt(6)
	v_mfma_f32_32x32x16_bf16 v[16:31], v[166:169], v[228:231], v[16:31]
	s_waitcnt lgkmcnt(4)
	v_mfma_f32_32x32x16_bf16 v[16:31], v[170:173], v[232:235], v[16:31]
	s_waitcnt lgkmcnt(2)
	v_mfma_f32_32x32x16_bf16 v[16:31], v[176:179], v[236:239], v[16:31]
	s_waitcnt lgkmcnt(0)
	v_mfma_f32_32x32x16_bf16 v[16:31], v[180:183], v[240:243], v[16:31]
	s_setprio 0
	s_barrier
	v_max3_f32 v190, v80, v81, v82
	v_max3_f32 v191, v64, v65, v66
	v_max3_f32 v190, v190, v83, v84
	v_max3_f32 v191, v191, v67, v68
	v_max3_f32 v190, v190, v85, v86
	v_max3_f32 v191, v191, v69, v70
	v_max3_f32 v190, v190, v87, v88
	v_max3_f32 v191, v191, v71, v72
	v_max3_f32 v190, v190, v89, v90
	v_max3_f32 v191, v191, v73, v74
	v_max3_f32 v190, v190, v91, v92
	v_max3_f32 v191, v191, v75, v76
	v_max3_f32 v190, v190, v93, v94
	v_max3_f32 v191, v191, v77, v78
	v_max3_f32 v190, v190, v95, v79
	v_max_f32_e32 v190, v190, v191
	v_sub_f32_e32 v215, v190, v174
	v_cmp_ge_f32_e32 vcc, s86, v215
	s_nop 0
	s_cmp_eq_u64 vcc, exec
	s_cbranch_scc1 .Lda_common_2
; __device__ __forceinline__ void partialSM(f32x16& p0, f32x16& p1, float& m_reg, float& mn, float& alpha) {
;     ...
;   if (__builtin_expect(__all(pmax - m_reg <= THR / SCALE), 1)) { mn = m_reg; alpha = 1.f; }
;   else { mn = fmaxf(m_reg, pmax); alpha = __builtin_amdgcn_exp2f((m_reg - mn) * C); m_reg = mn; }
;   float mnC = -mn * C;
; #pragma unroll
;   for (int r = 0; r < 16; ++r) p0[r] = fmaf(p0[r], C, mnC);
; #pragma unroll
;   for (int r = 0; r < 16; ++r) p1[r] = fmaf(p1[r], C, mnC);
; #pragma unroll
;   for (int r = 0; r < 16; ++r) p0[r] = __builtin_amdgcn_exp2f(p0[r]);
; }
; __device__ __forceinline__ void finishSM(f32x16& p0, f32x16& p1, float alpha, float& l_reg, bf16x8& pa0, bf16x8& pa1, bf16x8& pa2, bf16x8& pa3) {
; #pragma unroll
;   for (int r = 0; r < 16; ++r) p1[r] = __builtin_amdgcn_exp2f(p1[r]);
;   float ps = 0;
; #pragma unroll
;   for (int r = 0; r < 16; ++r) ps += p0[r];
; #pragma unroll
;   for (int r = 0; r < 16; ++r) ps += p1[r];
;   { auto rr = __builtin_amdgcn_permlane32_swap(__float_as_uint(ps), __float_as_uint(ps), false, false);
;     ps = __uint_as_float(rr[0]) + __uint_as_float(rr[1]); }
;   l_reg = l_reg * alpha + ps;
;     ...
;   PK4(p0, 0, pa0); PK4(p0, 8, pa1); PK4(p1, 0, pa2); PK4(p1, 8, pa3);
;     ...
; }
	v_mov_b32_e32 v191, v190
	s_nop 1
	v_permlane32_swap_b32_e32 v190, v191
	s_nop 0
	v_max_f32_e32 v212, v190, v191
	v_max_f32_e32 v191, v174, v212
	v_sub_f32_e32 v215, v174, v191
	v_mul_f32_e32 v215, s92, v215
	v_exp_f32_e32 v213, v215
	v_mov_b32_e32 v174, v191
	v_mul_f32_e32 v214, 0xbe0293ee, v174
	v_mul_f32_e32 v175, v175, v213
	s_and_saveexec_b64 s[12:13], s[40:41]
	ds_write_b32 v199, v213 offset:128
	s_or_b64 exec, exec, s[12:13]
	s_waitcnt lgkmcnt(0)
	v_add_u32_e32 v215, v99, v96
	ds_read_b128 v[228:231], v215 offset:128
	ds_read_b128 v[232:235], v215 offset:160
	ds_read_b128 v[236:239], v215 offset:192
	ds_read_b128 v[240:243], v215 offset:224
	s_waitcnt lgkmcnt(0)
	v_pk_mul_f32 v[0:1], v[0:1], v[228:229]
	v_pk_mul_f32 v[2:3], v[2:3], v[230:231]
	v_pk_mul_f32 v[4:5], v[4:5], v[232:233]
	v_pk_mul_f32 v[6:7], v[6:7], v[234:235]
	v_pk_mul_f32 v[8:9], v[8:9], v[236:237]
	v_pk_mul_f32 v[10:11], v[10:11], v[238:239]
	v_pk_mul_f32 v[12:13], v[12:13], v[240:241]
	v_pk_mul_f32 v[14:15], v[14:15], v[242:243]
	v_pk_mul_f32 v[48:49], v[48:49], v[228:229]
	v_pk_mul_f32 v[50:51], v[50:51], v[230:231]
	v_pk_mul_f32 v[52:53], v[52:53], v[232:233]
	v_pk_mul_f32 v[54:55], v[54:55], v[234:235]
	v_pk_mul_f32 v[56:57], v[56:57], v[236:237]
	v_pk_mul_f32 v[58:59], v[58:59], v[238:239]
	v_pk_mul_f32 v[60:61], v[60:61], v[240:241]
	v_pk_mul_f32 v[62:63], v[62:63], v[242:243]
	v_pk_mul_f32 v[32:33], v[32:33], v[228:229]
	v_pk_mul_f32 v[34:35], v[34:35], v[230:231]
	v_pk_mul_f32 v[36:37], v[36:37], v[232:233]
	v_pk_mul_f32 v[38:39], v[38:39], v[234:235]
	v_pk_mul_f32 v[40:41], v[40:41], v[236:237]
	v_pk_mul_f32 v[42:43], v[42:43], v[238:239]
	v_pk_mul_f32 v[44:45], v[44:45], v[240:241]
	v_pk_mul_f32 v[46:47], v[46:47], v[242:243]
	v_pk_mul_f32 v[16:17], v[16:17], v[228:229]
	v_pk_mul_f32 v[18:19], v[18:19], v[230:231]
	v_pk_mul_f32 v[20:21], v[20:21], v[232:233]
	v_pk_mul_f32 v[22:23], v[22:23], v[234:235]
	v_pk_mul_f32 v[24:25], v[24:25], v[236:237]
	v_pk_mul_f32 v[26:27], v[26:27], v[238:239]
	v_pk_mul_f32 v[28:29], v[28:29], v[240:241]
	v_pk_mul_f32 v[30:31], v[30:31], v[242:243]
.Lda_common_2:
	s_cmp_lt_u32 s31, 131
	s_cbranch_scc0 .Lda_skipk_2
	ds_read_b128 v[150:153], v204 offset:49152
	ds_read_b128 v[154:157], v204 offset:57344
	ds_read_b128 v[158:161], v205 offset:49152
	ds_read_b128 v[162:165], v205 offset:57344
	ds_read_b128 v[228:231], v206 offset:49152
	ds_read_b128 v[232:235], v206 offset:57344
	ds_read_b128 v[236:239], v207 offset:49152
	ds_read_b128 v[240:243], v207 offset:57344
.Lda_skipk_2:
	v_fma_f32 v80, v80, s92, v214
	v_fma_f32 v81, v81, s92, v214
	v_fma_f32 v82, v82, s92, v214
	v_fma_f32 v83, v83, s92, v214
	v_fma_f32 v84, v84, s92, v214
	v_fma_f32 v85, v85, s92, v214
	v_fma_f32 v86, v86, s92, v214
	v_fma_f32 v87, v87, s92, v214
	v_fma_f32 v88, v88, s92, v214
	v_fma_f32 v89, v89, s92, v214
	v_fma_f32 v90, v90, s92, v214
	v_fma_f32 v91, v91, s92, v214
	v_fma_f32 v92, v92, s92, v214
	v_fma_f32 v93, v93, s92, v214
	v_fma_f32 v94, v94, s92, v214
	v_fma_f32 v95, v95, s92, v214
	v_fma_f32 v64, v64, s92, v214
	v_fma_f32 v65, v65, s92, v214
	v_fma_f32 v66, v66, s92, v214
	v_fma_f32 v67, v67, s92, v214
	v_fma_f32 v68, v68, s92, v214
	v_fma_f32 v69, v69, s92, v214
	v_fma_f32 v70, v70, s92, v214
	v_fma_f32 v71, v71, s92, v214
	v_fma_f32 v72, v72, s92, v214
	v_fma_f32 v73, v73, s92, v214
	v_fma_f32 v74, v74, s92, v214
	v_fma_f32 v75, v75, s92, v214
	v_fma_f32 v76, v76, s92, v214
	v_fma_f32 v77, v77, s92, v214
	v_fma_f32 v78, v78, s92, v214
	v_fma_f32 v79, v79, s92, v214
.Lda_noresc_2:
	v_exp_f32_e32 v80, v80
	v_exp_f32_e32 v81, v81
	v_exp_f32_e32 v82, v82
	v_exp_f32_e32 v83, v83
	v_exp_f32_e32 v84, v84
	v_exp_f32_e32 v85, v85
	v_exp_f32_e32 v86, v86
	v_exp_f32_e32 v87, v87
	v_exp_f32_e32 v88, v88
	v_exp_f32_e32 v89, v89
	v_exp_f32_e32 v90, v90
	v_exp_f32_e32 v91, v91
	v_exp_f32_e32 v92, v92
	v_exp_f32_e32 v93, v93
	v_exp_f32_e32 v94, v94
	v_exp_f32_e32 v95, v95
	v_exp_f32_e32 v64, v64
	v_exp_f32_e32 v65, v65
	v_exp_f32_e32 v66, v66
	v_exp_f32_e32 v67, v67
	v_exp_f32_e32 v68, v68
	v_exp_f32_e32 v69, v69
	v_exp_f32_e32 v70, v70
	v_exp_f32_e32 v71, v71
	v_exp_f32_e32 v72, v72
	v_exp_f32_e32 v73, v73
	v_exp_f32_e32 v74, v74
	v_exp_f32_e32 v75, v75
	v_exp_f32_e32 v76, v76
	v_exp_f32_e32 v77, v77
	v_exp_f32_e32 v78, v78
	v_exp_f32_e32 v79, v79
	v_add_f32_e32 v190, v80, v81
	v_add_f32_e32 v191, v82, v83
	v_add_f32_e32 v190, v190, v84
	v_add_f32_e32 v191, v191, v85
	v_add_f32_e32 v190, v190, v86
	v_add_f32_e32 v191, v191, v87
	v_add_f32_e32 v190, v190, v88
	v_add_f32_e32 v191, v191, v89
	v_add_f32_e32 v190, v190, v90
	v_add_f32_e32 v191, v191, v91
	v_add_f32_e32 v190, v190, v92
	v_add_f32_e32 v191, v191, v93
	v_add_f32_e32 v190, v190, v94
	v_add_f32_e32 v191, v191, v95
	v_add_f32_e32 v190, v190, v64
	v_add_f32_e32 v191, v191, v65
	v_add_f32_e32 v190, v190, v66
	v_add_f32_e32 v191, v191, v67
	v_add_f32_e32 v190, v190, v68
	v_add_f32_e32 v191, v191, v69
	v_add_f32_e32 v190, v190, v70
	v_add_f32_e32 v191, v191, v71
	v_add_f32_e32 v190, v190, v72
	v_add_f32_e32 v191, v191, v73
	v_add_f32_e32 v190, v190, v74
	v_add_f32_e32 v191, v191, v75
	v_add_f32_e32 v190, v190, v76
	v_add_f32_e32 v191, v191, v77
	v_add_f32_e32 v190, v190, v78
	v_add_f32_e32 v191, v191, v79
	v_add_f32_e32 v190, v190, v191
	v_cvt_pk_bf16_f32 v166, v80, v81
	v_cvt_pk_bf16_f32 v167, v82, v83
	v_cvt_pk_bf16_f32 v168, v84, v85
	v_cvt_pk_bf16_f32 v169, v86, v87
	v_cvt_pk_bf16_f32 v170, v88, v89
	v_cvt_pk_bf16_f32 v171, v90, v91
	v_cvt_pk_bf16_f32 v172, v92, v93
	v_cvt_pk_bf16_f32 v173, v94, v95
	v_cvt_pk_bf16_f32 v176, v64, v65
	v_cvt_pk_bf16_f32 v177, v66, v67
	v_cvt_pk_bf16_f32 v178, v68, v69
	v_cvt_pk_bf16_f32 v179, v70, v71
	v_cvt_pk_bf16_f32 v180, v72, v73
	v_cvt_pk_bf16_f32 v181, v74, v75
	v_cvt_pk_bf16_f32 v182, v76, v77
	v_cvt_pk_bf16_f32 v183, v78, v79
	v_permlane32_swap_b32_e32 v166, v168
	v_permlane32_swap_b32_e32 v167, v169
	v_permlane32_swap_b32_e32 v170, v172
	v_permlane32_swap_b32_e32 v171, v173
	v_permlane32_swap_b32_e32 v176, v178
	v_permlane32_swap_b32_e32 v177, v179
	v_permlane32_swap_b32_e32 v180, v182
	v_permlane32_swap_b32_e32 v181, v183
	v_add_f32_e32 v175, v175, v190
	s_add_u32 s31, s31, 1
	s_barrier
; #define SBAR() __builtin_amdgcn_sched_barrier(0)
; __device__ __forceinline__ void qkt(f32x16& p0, f32x16& p1, const bf16_t* Ks, const bf16x8* qr, int r32, int hi) {
;   p0 = f32x16{}; p1 = f32x16{};
; #pragma unroll
;   for (int d0 = 0; d0 < 8; ++d0) { int cb = (d0 * 16 + hi * 8) * 2;
;     bf16x8 b0 = *reinterpret_cast<const bf16x8*>((const char*)Ks + KSWZ(r32, cb));
;     bf16x8 b1 = *reinterpret_cast<const bf16x8*>((const char*)Ks + KSWZ(32 + r32, cb));
;     p0 = __builtin_amdgcn_mfma_f32_32x32x16_bf16(b0, qr[d0], p0, 0, 0, 0);
;     p1 = __builtin_amdgcn_mfma_f32_32x32x16_bf16(b1, qr[d0], p1, 0, 0, 0); }
; }
; __device__ __forceinline__ int v_st(int k, int c) { const int kk = (k & ~0xC) | ((k & 4) << 1) | ((k & 8) >> 1); return ((kk >> 3) * 4 + (c >> 5)) * 512 + ((kk & 7) * 32 + (c & 31)) * 2; }
; __device__ __forceinline__ int v_rd_base(int lane) { return ((lane & 3) << 3) | (((lane >> 2) & 3) << 6) | (((lane >> 4) & 1) << 5) | (((lane >> 5) & 1) << 8); }
; template <int OFF> __device__ __forceinline__ s16x4 tr_read(int vb) {
;   s16x4 r; asm volatile("ds_read_b64_tr_b16 %0, %1 offset:%2" : "=&v"(r) : "v"(vb), "i"(OFF) : "memory"); return r;
; }
; template <int D0> __device__ __forceinline__ void pv_one(f32x16& od, int vb, bf16x8 pa0, bf16x8 pa1, bf16x8 pa2, bf16x8 pa3) {
;   const s16x4 l0 = tr_read<v_rd_off(D0, 0, 0)>(vb), h0 = tr_read<v_rd_off(D0, 0, 1)>(vb), l1 = tr_read<v_rd_off(D0, 1, 0)>(vb), h1 = tr_read<v_rd_off(D0, 1, 1)>(vb);
;   const s16x4 l2 = tr_read<v_rd_off(D0, 2, 0)>(vb), h2 = tr_read<v_rd_off(D0, 2, 1)>(vb), l3 = tr_read<v_rd_off(D0, 3, 0)>(vb), h3 = tr_read<v_rd_off(D0, 3, 1)>(vb);
;   asm volatile("s_waitcnt lgkmcnt(0)" ::: "memory"); SBAR();
;     ...
;   od = __builtin_amdgcn_mfma_f32_32x32x16_bf16(pa0, PK(l0, h0), od, 0, 0, 0);
;   od = __builtin_amdgcn_mfma_f32_32x32x16_bf16(pa1, PK(l1, h1), od, 0, 0, 0);
;   od = __builtin_amdgcn_mfma_f32_32x32x16_bf16(pa2, PK(l2, h2), od, 0, 0, 0);
;   od = __builtin_amdgcn_mfma_f32_32x32x16_bf16(pa3, PK(l3, h3), od, 0, 0, 0);
;     ...
; }
; __device__ __forceinline__ void pv_d0(f32x16* o, int vb, bf16x8 pa0, bf16x8 pa1, bf16x8 pa2, bf16x8 pa3) {
;   pv_one<0>(o[0], vb, pa0, pa1, pa2, pa3); pv_one<1>(o[1], vb, pa0, pa1, pa2, pa3); pv_one<2>(o[2], vb, pa0, pa1, pa2, pa3); pv_one<3>(o[3], vb, pa0, pa1, pa2, pa3);
	s_setprio 3
	s_waitcnt vmcnt(4)
	ds_write_b128 v197, v[186:189] offset:16384
	ds_write_b128 v197, v[220:223] offset:24576
	ds_write_b128 v185, v[246:249] offset:16384
	ds_write_b128 v185, v[200:203] offset:24576
	s_waitcnt lgkmcnt(10)
	v_mfma_f32_32x32x16_bf16 v[80:95], v[150:153], v[130:133], 0
	v_mfma_f32_32x32x16_bf16 v[64:79], v[154:157], v[130:133], 0
	global_load_dwordx4 v[186:189], v184, s[16:17]
	global_load_dwordx4 v[220:223], v184, s[2:3]
	global_load_dwordx4 v[246:249], v184, s[14:15]
	global_load_dwordx4 v[200:203], v184, s[10:11]
	s_add_u32 s16, s16, 0x60000
	s_addc_u32 s17, s17, 0
	s_add_u32 s2, s2, 0x60000
	s_addc_u32 s3, s3, 0
	s_add_u32 s14, s14, 0x60000
	s_addc_u32 s15, s15, 0
	s_add_u32 s10, s10, 0x60000
	s_addc_u32 s11, s11, 0
	ds_read_b128 v[150:153], v208 offset:49152
	ds_read_b128 v[154:157], v208 offset:57344
	s_waitcnt lgkmcnt(10)
	v_mfma_f32_32x32x16_bf16 v[80:95], v[158:161], v[126:129], v[80:95]
	v_mfma_f32_32x32x16_bf16 v[64:79], v[162:165], v[126:129], v[64:79]
	ds_read_b128 v[158:161], v209 offset:49152
	ds_read_b128 v[162:165], v209 offset:57344
	s_waitcnt lgkmcnt(10)
	v_mfma_f32_32x32x16_bf16 v[80:95], v[228:231], v[122:125], v[80:95]
	v_mfma_f32_32x32x16_bf16 v[64:79], v[232:235], v[122:125], v[64:79]
	ds_read_b128 v[228:231], v210 offset:49152
	ds_read_b128 v[232:235], v210 offset:57344
	s_waitcnt lgkmcnt(10)
	v_mfma_f32_32x32x16_bf16 v[80:95], v[236:239], v[118:121], v[80:95]
	v_mfma_f32_32x32x16_bf16 v[64:79], v[240:243], v[118:121], v[64:79]
	ds_read_b128 v[236:239], v211 offset:49152
	ds_read_b128 v[240:243], v211 offset:57344
	s_waitcnt lgkmcnt(6)
	v_mfma_f32_32x32x16_bf16 v[80:95], v[150:153], v[114:117], v[80:95]
	v_mfma_f32_32x32x16_bf16 v[64:79], v[154:157], v[114:117], v[64:79]
	ds_read_b64_tr_b16 v[150:151], v196 offset:32768
	ds_read_b64_tr_b16 v[152:153], v196 offset:34816
	ds_read_b64_tr_b16 v[154:155], v196 offset:36864
	ds_read_b64_tr_b16 v[156:157], v196 offset:38912
	s_waitcnt lgkmcnt(8)
	v_mfma_f32_32x32x16_bf16 v[80:95], v[158:161], v[110:113], v[80:95]
	v_mfma_f32_32x32x16_bf16 v[64:79], v[162:165], v[110:113], v[64:79]
	ds_read_b64_tr_b16 v[158:159], v196 offset:40960
	ds_read_b64_tr_b16 v[160:161], v196 offset:43008
	ds_read_b64_tr_b16 v[162:163], v196 offset:45056
	ds_read_b64_tr_b16 v[164:165], v196 offset:47104
	s_waitcnt lgkmcnt(10)
	v_mfma_f32_32x32x16_bf16 v[80:95], v[228:231], v[106:109], v[80:95]
	v_mfma_f32_32x32x16_bf16 v[64:79], v[232:235], v[106:109], v[64:79]
	ds_read_b64_tr_b16 v[228:229], v196 offset:33280
	ds_read_b64_tr_b16 v[230:231], v196 offset:35328
	ds_read_b64_tr_b16 v[232:233], v196 offset:37376
	ds_read_b64_tr_b16 v[234:235], v196 offset:39424
	s_waitcnt lgkmcnt(12)
	v_mfma_f32_32x32x16_bf16 v[80:95], v[236:239], v[102:105], v[80:95]
	v_mfma_f32_32x32x16_bf16 v[64:79], v[240:243], v[102:105], v[64:79]
	ds_read_b64_tr_b16 v[236:237], v196 offset:41472
	ds_read_b64_tr_b16 v[238:239], v196 offset:43520
	s_waitcnt lgkmcnt(12)
	v_mfma_f32_32x32x16_bf16 v[0:15], v[166:169], v[150:153], v[0:15]
	ds_read_b64_tr_b16 v[240:241], v196 offset:45568
	ds_read_b64_tr_b16 v[242:243], v196 offset:47616
	s_waitcnt lgkmcnt(12)
	v_mfma_f32_32x32x16_bf16 v[0:15], v[170:173], v[154:157], v[0:15]
	ds_read_b64_tr_b16 v[150:151], v196 offset:33792
	ds_read_b64_tr_b16 v[152:153], v196 offset:35840
	s_waitcnt lgkmcnt(12)
	v_mfma_f32_32x32x16_bf16 v[0:15], v[176:179], v[158:161], v[0:15]
	ds_read_b64_tr_b16 v[154:155], v196 offset:37888
	ds_read_b64_tr_b16 v[156:157], v196 offset:39936
	s_waitcnt lgkmcnt(12)
	v_mfma_f32_32x32x16_bf16 v[0:15], v[180:183], v[162:165], v[0:15]
	ds_read_b64_tr_b16 v[158:159], v196 offset:41984
	ds_read_b64_tr_b16 v[160:161], v196 offset:44032
	s_waitcnt lgkmcnt(12)
	v_mfma_f32_32x32x16_bf16 v[48:63], v[166:169], v[228:231], v[48:63]
	ds_read_b64_tr_b16 v[162:163], v196 offset:46080
	ds_read_b64_tr_b16 v[164:165], v196 offset:48128
	s_waitcnt lgkmcnt(12)
	v_mfma_f32_32x32x16_bf16 v[48:63], v[170:173], v[232:235], v[48:63]
	ds_read_b64_tr_b16 v[228:229], v196 offset:34304
	ds_read_b64_tr_b16 v[230:231], v196 offset:36352
	s_waitcnt lgkmcnt(12)
	v_mfma_f32_32x32x16_bf16 v[48:63], v[176:179], v[236:239], v[48:63]
	ds_read_b64_tr_b16 v[232:233], v196 offset:38400
	ds_read_b64_tr_b16 v[234:235], v196 offset:40448
	s_waitcnt lgkmcnt(12)
	v_mfma_f32_32x32x16_bf16 v[48:63], v[180:183], v[240:243], v[48:63]
	ds_read_b64_tr_b16 v[236:237], v196 offset:42496
	ds_read_b64_tr_b16 v[238:239], v196 offset:44544
	s_waitcnt lgkmcnt(12)
	v_mfma_f32_32x32x16_bf16 v[32:47], v[166:169], v[150:153], v[32:47]
	ds_read_b64_tr_b16 v[240:241], v196 offset:46592
	ds_read_b64_tr_b16 v[242:243], v196 offset:48640
	s_waitcnt lgkmcnt(12)
	v_mfma_f32_32x32x16_bf16 v[32:47], v[170:173], v[154:157], v[32:47]
	s_waitcnt lgkmcnt(10)
	v_mfma_f32_32x32x16_bf16 v[32:47], v[176:179], v[158:161], v[32:47]
	s_waitcnt lgkmcnt(8)
	v_mfma_f32_32x32x16_bf16 v[32:47], v[180:183], v[162:165], v[32:47]
	s_waitcnt lgkmcnt(6)
	v_mfma_f32_32x32x16_bf16 v[16:31], v[166:169], v[228:231], v[16:31]
	s_waitcnt lgkmcnt(4)
	v_mfma_f32_32x32x16_bf16 v[16:31], v[170:173], v[232:235], v[16:31]
	s_waitcnt lgkmcnt(2)
	v_mfma_f32_32x32x16_bf16 v[16:31], v[176:179], v[236:239], v[16:31]
	s_waitcnt lgkmcnt(0)
	v_mfma_f32_32x32x16_bf16 v[16:31], v[180:183], v[240:243], v[16:31]
	s_setprio 0
	s_barrier
; __device__ __forceinline__ void partialSM(f32x16& p0, f32x16& p1, float& m_reg, float& mn, float& alpha) {
;   constexpr float C = SCALE * 1.4426950408889634f;
;   float pmax = p0[0];
; #pragma unroll
;   for (int r = 1; r < 16; ++r) pmax = fmaxf(pmax, p0[r]);
; #pragma unroll
;   for (int r = 0; r < 16; ++r) pmax = fmaxf(pmax, p1[r]);
;   { auto rr = __builtin_amdgcn_permlane32_swap(__float_as_uint(pmax), __float_as_uint(pmax), false, false);
;     pmax = fmaxf(__uint_as_float(rr[0]), __uint_as_float(rr[1])); }
;   if (__builtin_expect(__all(pmax - m_reg <= THR / SCALE), 1)) { mn = m_reg; alpha = 1.f; }
;   else { mn = fmaxf(m_reg, pmax); alpha = __builtin_amdgcn_exp2f((m_reg - mn) * C); m_reg = mn; }
;   float mnC = -mn * C;
; #pragma unroll
;   for (int r = 0; r < 16; ++r) p0[r] = fmaf(p0[r], C, mnC);
; #pragma unroll
;   for (int r = 0; r < 16; ++r) p1[r] = fmaf(p1[r], C, mnC);
	v_max3_f32 v190, v80, v81, v82
	v_max3_f32 v191, v64, v65, v66
	v_max3_f32 v190, v190, v83, v84
	v_max3_f32 v191, v191, v67, v68
	v_max3_f32 v190, v190, v85, v86
	v_max3_f32 v191, v191, v69, v70
	v_max3_f32 v190, v190, v87, v88
	v_max3_f32 v191, v191, v71, v72
	v_max3_f32 v190, v190, v89, v90
	v_max3_f32 v191, v191, v73, v74
	v_max3_f32 v190, v190, v91, v92
	v_max3_f32 v191, v191, v75, v76
	v_max3_f32 v190, v190, v93, v94
	v_max3_f32 v191, v191, v77, v78
	v_max3_f32 v190, v190, v95, v79
	v_max_f32_e32 v190, v190, v191
	v_sub_f32_e32 v215, v190, v174
	v_cmp_ge_f32_e32 vcc, s86, v215
	s_nop 0
	s_cmp_eq_u64 vcc, exec
	s_cbranch_scc1 .Lda_common_3
	v_mov_b32_e32 v191, v190
	s_nop 1
	v_permlane32_swap_b32_e32 v190, v191
	s_nop 0
	v_max_f32_e32 v212, v190, v191
	v_max_f32_e32 v191, v174, v212
	v_sub_f32_e32 v215, v174, v191
	v_mul_f32_e32 v215, s92, v215
	v_exp_f32_e32 v213, v215
	v_mov_b32_e32 v174, v191
	v_mul_f32_e32 v214, 0xbe0293ee, v174
	v_mul_f32_e32 v175, v175, v213
	s_and_saveexec_b64 s[12:13], s[40:41]
	ds_write_b32 v199, v213 offset:128
	s_or_b64 exec, exec, s[12:13]
	s_waitcnt lgkmcnt(0)
	v_add_u32_e32 v215, v99, v96
	ds_read_b128 v[228:231], v215 offset:128
	ds_read_b128 v[232:235], v215 offset:160
	ds_read_b128 v[236:239], v215 offset:192
	ds_read_b128 v[240:243], v215 offset:224
	s_waitcnt lgkmcnt(0)
	v_pk_mul_f32 v[0:1], v[0:1], v[228:229]
	v_pk_mul_f32 v[2:3], v[2:3], v[230:231]
	v_pk_mul_f32 v[4:5], v[4:5], v[232:233]
	v_pk_mul_f32 v[6:7], v[6:7], v[234:235]
	v_pk_mul_f32 v[8:9], v[8:9], v[236:237]
	v_pk_mul_f32 v[10:11], v[10:11], v[238:239]
	v_pk_mul_f32 v[12:13], v[12:13], v[240:241]
	v_pk_mul_f32 v[14:15], v[14:15], v[242:243]
	v_pk_mul_f32 v[48:49], v[48:49], v[228:229]
	v_pk_mul_f32 v[50:51], v[50:51], v[230:231]
	v_pk_mul_f32 v[52:53], v[52:53], v[232:233]
	v_pk_mul_f32 v[54:55], v[54:55], v[234:235]
	v_pk_mul_f32 v[56:57], v[56:57], v[236:237]
	v_pk_mul_f32 v[58:59], v[58:59], v[238:239]
	v_pk_mul_f32 v[60:61], v[60:61], v[240:241]
	v_pk_mul_f32 v[62:63], v[62:63], v[242:243]
	v_pk_mul_f32 v[32:33], v[32:33], v[228:229]
	v_pk_mul_f32 v[34:35], v[34:35], v[230:231]
	v_pk_mul_f32 v[36:37], v[36:37], v[232:233]
	v_pk_mul_f32 v[38:39], v[38:39], v[234:235]
	v_pk_mul_f32 v[40:41], v[40:41], v[236:237]
	v_pk_mul_f32 v[42:43], v[42:43], v[238:239]
	v_pk_mul_f32 v[44:45], v[44:45], v[240:241]
	v_pk_mul_f32 v[46:47], v[46:47], v[242:243]
	v_pk_mul_f32 v[16:17], v[16:17], v[228:229]
	v_pk_mul_f32 v[18:19], v[18:19], v[230:231]
	v_pk_mul_f32 v[20:21], v[20:21], v[232:233]
	v_pk_mul_f32 v[22:23], v[22:23], v[234:235]
	v_pk_mul_f32 v[24:25], v[24:25], v[236:237]
	v_pk_mul_f32 v[26:27], v[26:27], v[238:239]
	v_pk_mul_f32 v[28:29], v[28:29], v[240:241]
	v_pk_mul_f32 v[30:31], v[30:31], v[242:243]
.Lda_common_3:
	s_cmp_lt_u32 s31, 131
	s_cbranch_scc0 .Lda_skipk_3
	ds_read_b128 v[150:153], v204 offset:0
	ds_read_b128 v[154:157], v204 offset:8192
	ds_read_b128 v[158:161], v205 offset:0
	ds_read_b128 v[162:165], v205 offset:8192
	ds_read_b128 v[228:231], v206 offset:0
	ds_read_b128 v[232:235], v206 offset:8192
	ds_read_b128 v[236:239], v207 offset:0
	ds_read_b128 v[240:243], v207 offset:8192
.Lda_skipk_3:
	v_fma_f32 v80, v80, s92, v214
	v_fma_f32 v81, v81, s92, v214
	v_fma_f32 v82, v82, s92, v214
	v_fma_f32 v83, v83, s92, v214
	v_fma_f32 v84, v84, s92, v214
	v_fma_f32 v85, v85, s92, v214
	v_fma_f32 v86, v86, s92, v214
	v_fma_f32 v87, v87, s92, v214
	v_fma_f32 v88, v88, s92, v214
	v_fma_f32 v89, v89, s92, v214
	v_fma_f32 v90, v90, s92, v214
	v_fma_f32 v91, v91, s92, v214
	v_fma_f32 v92, v92, s92, v214
	v_fma_f32 v93, v93, s92, v214
	v_fma_f32 v94, v94, s92, v214
	v_fma_f32 v95, v95, s92, v214
	v_fma_f32 v64, v64, s92, v214
	v_fma_f32 v65, v65, s92, v214
	v_fma_f32 v66, v66, s92, v214
	v_fma_f32 v67, v67, s92, v214
	v_fma_f32 v68, v68, s92, v214
	v_fma_f32 v69, v69, s92, v214
	v_fma_f32 v70, v70, s92, v214
	v_fma_f32 v71, v71, s92, v214
	v_fma_f32 v72, v72, s92, v214
	v_fma_f32 v73, v73, s92, v214
	v_fma_f32 v74, v74, s92, v214
	v_fma_f32 v75, v75, s92, v214
	v_fma_f32 v76, v76, s92, v214
	v_fma_f32 v77, v77, s92, v214
	v_fma_f32 v78, v78, s92, v214
	v_fma_f32 v79, v79, s92, v214
; #define SBAR() __builtin_amdgcn_sched_barrier(0)
; __device__ __forceinline__ void partialSM(f32x16& p0, f32x16& p1, float& m_reg, float& mn, float& alpha) {
;     ...
;   for (int r = 0; r < 16; ++r) p0[r] = __builtin_amdgcn_exp2f(p0[r]);
; }
; __device__ __forceinline__ void finishSM(f32x16& p0, f32x16& p1, float alpha, float& l_reg, bf16x8& pa0, bf16x8& pa1, bf16x8& pa2, bf16x8& pa3) {
; #pragma unroll
;   for (int r = 0; r < 16; ++r) p1[r] = __builtin_amdgcn_exp2f(p1[r]);
;   float ps = 0;
; #pragma unroll
;   for (int r = 0; r < 16; ++r) ps += p0[r];
; #pragma unroll
;   for (int r = 0; r < 16; ++r) ps += p1[r];
;   { auto rr = __builtin_amdgcn_permlane32_swap(__float_as_uint(ps), __float_as_uint(ps), false, false);
;     ps = __uint_as_float(rr[0]) + __uint_as_float(rr[1]); }
;   l_reg = l_reg * alpha + ps;
;     ...
;   PK4(p0, 0, pa0); PK4(p0, 8, pa1); PK4(p1, 0, pa2); PK4(p1, 8, pa3);
;     ...
; }
; template <int D0> __device__ __forceinline__ void pv_one(f32x16& od, int vb, bf16x8 pa0, bf16x8 pa1, bf16x8 pa2, bf16x8 pa3) {
;   const s16x4 l0 = tr_read<v_rd_off(D0, 0, 0)>(vb), h0 = tr_read<v_rd_off(D0, 0, 1)>(vb), l1 = tr_read<v_rd_off(D0, 1, 0)>(vb), h1 = tr_read<v_rd_off(D0, 1, 1)>(vb);
;   const s16x4 l2 = tr_read<v_rd_off(D0, 2, 0)>(vb), h2 = tr_read<v_rd_off(D0, 2, 1)>(vb), l3 = tr_read<v_rd_off(D0, 3, 0)>(vb), h3 = tr_read<v_rd_off(D0, 3, 1)>(vb);
;   asm volatile("s_waitcnt lgkmcnt(0)" ::: "memory"); SBAR();
;     ...
;   od = __builtin_amdgcn_mfma_f32_32x32x16_bf16(pa0, PK(l0, h0), od, 0, 0, 0);
;   od = __builtin_amdgcn_mfma_f32_32x32x16_bf16(pa1, PK(l1, h1), od, 0, 0, 0);
;   od = __builtin_amdgcn_mfma_f32_32x32x16_bf16(pa2, PK(l2, h2), od, 0, 0, 0);
;   od = __builtin_amdgcn_mfma_f32_32x32x16_bf16(pa3, PK(l3, h3), od, 0, 0, 0);
;     ...
; }
; __device__ __forceinline__ void pv_d0(f32x16* o, int vb, bf16x8 pa0, bf16x8 pa1, bf16x8 pa2, bf16x8 pa3) {
;   pv_one<0>(o[0], vb, pa0, pa1, pa2, pa3); pv_one<1>(o[1], vb, pa0, pa1, pa2, pa3); pv_one<2>(o[2], vb, pa0, pa1, pa2, pa3); pv_one<3>(o[3], vb, pa0, pa1, pa2, pa3);
.Lda_noresc_3:
	v_exp_f32_e32 v80, v80
	v_exp_f32_e32 v81, v81
	v_exp_f32_e32 v82, v82
	v_exp_f32_e32 v83, v83
	v_exp_f32_e32 v84, v84
	v_exp_f32_e32 v85, v85
	v_exp_f32_e32 v86, v86
	v_exp_f32_e32 v87, v87
	v_exp_f32_e32 v88, v88
	v_exp_f32_e32 v89, v89
	v_exp_f32_e32 v90, v90
	v_exp_f32_e32 v91, v91
	v_exp_f32_e32 v92, v92
	v_exp_f32_e32 v93, v93
	v_exp_f32_e32 v94, v94
	v_exp_f32_e32 v95, v95
	v_exp_f32_e32 v64, v64
	v_exp_f32_e32 v65, v65
	v_exp_f32_e32 v66, v66
	v_exp_f32_e32 v67, v67
	v_exp_f32_e32 v68, v68
	v_exp_f32_e32 v69, v69
	v_exp_f32_e32 v70, v70
	v_exp_f32_e32 v71, v71
	v_exp_f32_e32 v72, v72
	v_exp_f32_e32 v73, v73
	v_exp_f32_e32 v74, v74
	v_exp_f32_e32 v75, v75
	v_exp_f32_e32 v76, v76
	v_exp_f32_e32 v77, v77
	v_exp_f32_e32 v78, v78
	v_exp_f32_e32 v79, v79
	v_add_f32_e32 v190, v80, v81
	v_add_f32_e32 v191, v82, v83
	v_add_f32_e32 v190, v190, v84
	v_add_f32_e32 v191, v191, v85
	v_add_f32_e32 v190, v190, v86
	v_add_f32_e32 v191, v191, v87
	v_add_f32_e32 v190, v190, v88
	v_add_f32_e32 v191, v191, v89
	v_add_f32_e32 v190, v190, v90
	v_add_f32_e32 v191, v191, v91
	v_add_f32_e32 v190, v190, v92
	v_add_f32_e32 v191, v191, v93
	v_add_f32_e32 v190, v190, v94
	v_add_f32_e32 v191, v191, v95
	v_add_f32_e32 v190, v190, v64
	v_add_f32_e32 v191, v191, v65
	v_add_f32_e32 v190, v190, v66
	v_add_f32_e32 v191, v191, v67
	v_add_f32_e32 v190, v190, v68
	v_add_f32_e32 v191, v191, v69
	v_add_f32_e32 v190, v190, v70
	v_add_f32_e32 v191, v191, v71
	v_add_f32_e32 v190, v190, v72
	v_add_f32_e32 v191, v191, v73
	v_add_f32_e32 v190, v190, v74
	v_add_f32_e32 v191, v191, v75
	v_add_f32_e32 v190, v190, v76
	v_add_f32_e32 v191, v191, v77
	v_add_f32_e32 v190, v190, v78
	v_add_f32_e32 v191, v191, v79
	v_add_f32_e32 v190, v190, v191
	v_cvt_pk_bf16_f32 v166, v80, v81
	v_cvt_pk_bf16_f32 v167, v82, v83
	v_cvt_pk_bf16_f32 v168, v84, v85
	v_cvt_pk_bf16_f32 v169, v86, v87
	v_cvt_pk_bf16_f32 v170, v88, v89
	v_cvt_pk_bf16_f32 v171, v90, v91
	v_cvt_pk_bf16_f32 v172, v92, v93
	v_cvt_pk_bf16_f32 v173, v94, v95
	v_cvt_pk_bf16_f32 v176, v64, v65
	v_cvt_pk_bf16_f32 v177, v66, v67
	v_cvt_pk_bf16_f32 v178, v68, v69
	v_cvt_pk_bf16_f32 v179, v70, v71
	v_cvt_pk_bf16_f32 v180, v72, v73
	v_cvt_pk_bf16_f32 v181, v74, v75
	v_cvt_pk_bf16_f32 v182, v76, v77
	v_cvt_pk_bf16_f32 v183, v78, v79
	v_permlane32_swap_b32_e32 v166, v168
	v_permlane32_swap_b32_e32 v167, v169
	v_permlane32_swap_b32_e32 v170, v172
	v_permlane32_swap_b32_e32 v171, v173
	v_permlane32_swap_b32_e32 v176, v178
	v_permlane32_swap_b32_e32 v177, v179
	v_permlane32_swap_b32_e32 v180, v182
	v_permlane32_swap_b32_e32 v181, v183
	v_add_f32_e32 v175, v175, v190
	s_add_u32 s31, s31, 1
	s_barrier
	s_cmp_lt_u32 s31, 132
	s_cbranch_scc1 .Lda_loop
	s_setprio 3
	ds_read_b64_tr_b16 v[150:151], v196 offset:49152
	ds_read_b64_tr_b16 v[152:153], v196 offset:51200
	ds_read_b64_tr_b16 v[154:155], v196 offset:53248
	ds_read_b64_tr_b16 v[156:157], v196 offset:55296
	ds_read_b64_tr_b16 v[158:159], v196 offset:57344
	ds_read_b64_tr_b16 v[160:161], v196 offset:59392
	ds_read_b64_tr_b16 v[162:163], v196 offset:61440
	ds_read_b64_tr_b16 v[164:165], v196 offset:63488
	ds_read_b64_tr_b16 v[228:229], v196 offset:49664
	ds_read_b64_tr_b16 v[230:231], v196 offset:51712
	ds_read_b64_tr_b16 v[232:233], v196 offset:53760
	ds_read_b64_tr_b16 v[234:235], v196 offset:55808
	ds_read_b64_tr_b16 v[236:237], v196 offset:57856
	ds_read_b64_tr_b16 v[238:239], v196 offset:59904
	s_waitcnt lgkmcnt(12)
	v_mfma_f32_32x32x16_bf16 v[0:15], v[166:169], v[150:153], v[0:15]
	ds_read_b64_tr_b16 v[240:241], v196 offset:61952
	ds_read_b64_tr_b16 v[242:243], v196 offset:64000
	s_waitcnt lgkmcnt(12)
	v_mfma_f32_32x32x16_bf16 v[0:15], v[170:173], v[154:157], v[0:15]
	ds_read_b64_tr_b16 v[150:151], v196 offset:50176
	ds_read_b64_tr_b16 v[152:153], v196 offset:52224
	s_waitcnt lgkmcnt(12)
	v_mfma_f32_32x32x16_bf16 v[0:15], v[176:179], v[158:161], v[0:15]
	ds_read_b64_tr_b16 v[154:155], v196 offset:54272
	ds_read_b64_tr_b16 v[156:157], v196 offset:56320
	s_waitcnt lgkmcnt(12)
	v_mfma_f32_32x32x16_bf16 v[0:15], v[180:183], v[162:165], v[0:15]
	ds_read_b64_tr_b16 v[158:159], v196 offset:58368
	ds_read_b64_tr_b16 v[160:161], v196 offset:60416
	s_waitcnt lgkmcnt(12)
	v_mfma_f32_32x32x16_bf16 v[48:63], v[166:169], v[228:231], v[48:63]
	ds_read_b64_tr_b16 v[162:163], v196 offset:62464
	ds_read_b64_tr_b16 v[164:165], v196 offset:64512
	s_waitcnt lgkmcnt(12)
	v_mfma_f32_32x32x16_bf16 v[48:63], v[170:173], v[232:235], v[48:63]
	ds_read_b64_tr_b16 v[228:229], v196 offset:50688
	ds_read_b64_tr_b16 v[230:231], v196 offset:52736
	s_waitcnt lgkmcnt(12)
	v_mfma_f32_32x32x16_bf16 v[48:63], v[176:179], v[236:239], v[48:63]
	ds_read_b64_tr_b16 v[232:233], v196 offset:54784
	ds_read_b64_tr_b16 v[234:235], v196 offset:56832
	s_waitcnt lgkmcnt(12)
	v_mfma_f32_32x32x16_bf16 v[48:63], v[180:183], v[240:243], v[48:63]
	ds_read_b64_tr_b16 v[236:237], v196 offset:58880
	ds_read_b64_tr_b16 v[238:239], v196 offset:60928
	s_waitcnt lgkmcnt(12)
	v_mfma_f32_32x32x16_bf16 v[32:47], v[166:169], v[150:153], v[32:47]
	ds_read_b64_tr_b16 v[240:241], v196 offset:62976
	ds_read_b64_tr_b16 v[242:243], v196 offset:65024
	s_waitcnt lgkmcnt(12)
	v_mfma_f32_32x32x16_bf16 v[32:47], v[170:173], v[154:157], v[32:47]
	s_waitcnt lgkmcnt(10)
	v_mfma_f32_32x32x16_bf16 v[32:47], v[176:179], v[158:161], v[32:47]
	s_waitcnt lgkmcnt(8)
	v_mfma_f32_32x32x16_bf16 v[32:47], v[180:183], v[162:165], v[32:47]
	s_waitcnt lgkmcnt(6)
	v_mfma_f32_32x32x16_bf16 v[16:31], v[166:169], v[228:231], v[16:31]
	s_waitcnt lgkmcnt(4)
	v_mfma_f32_32x32x16_bf16 v[16:31], v[170:173], v[232:235], v[16:31]
	s_waitcnt lgkmcnt(2)
	v_mfma_f32_32x32x16_bf16 v[16:31], v[176:179], v[236:239], v[16:31]
	s_waitcnt lgkmcnt(0)
	v_mfma_f32_32x32x16_bf16 v[16:31], v[180:183], v[240:243], v[16:31]
	s_nop 12
	s_setprio 0
	s_cmp_lt_u32 s36, 4
	s_cbranch_scc0 .Lda_trail
	s_barrier
